# MoBA gating score loop: LDS reads issued 12 ahead into a rotating register pool, original reads become counted wait + copy
# speedup vs baseline: 1.0015x; 1.0015x over previous
.LBB0_93:
	s_xor_b64 s[56:57], s[0:1], -1
	s_and_b64 s[0:1], s[0:1], exec
	s_cselect_b32 s8, s43, s44
	s_lshl_b32 s46, s8, 7
	s_ashr_i32 s1, s46, 31
	s_add_u32 s0, s46, s6
	s_addc_u32 s1, s1, 0
	v_lshl_add_u64 v[36:37], s[0:1], 0, v[116:117]
	v_mov_b64_e32 v[40:41], s[88:89]
	v_mad_u64_u32 v[38:39], s[10:11], v36, s72, v[40:41]
	v_mad_i32_i24 v39, v37, s72, v39
	s_lshl_b32 s20, s45, 1
	v_lshl_add_u64 v[36:37], v[38:39], 0, s[20:21]
	v_lshl_add_u64 v[36:37], v[36:37], 0, v[2:3]
	v_add_co_u32_e32 v36, vcc, s3, v36
	s_nop 1
	v_addc_co_u32_e32 v37, vcc, 0, v37, vcc
	global_load_dwordx4 v[4:7], v[36:37], off
	v_lshl_add_u64 v[36:37], s[0:1], 0, v[122:123]
	v_mad_u64_u32 v[38:39], s[10:11], v36, s72, v[40:41]
	v_mad_i32_i24 v39, v37, s72, v39
	v_lshl_add_u64 v[36:37], v[38:39], 0, s[20:21]
	v_lshl_add_u64 v[36:37], v[36:37], 0, v[2:3]
	v_add_co_u32_e32 v36, vcc, s3, v36
	s_nop 1
	v_addc_co_u32_e32 v37, vcc, 0, v37, vcc
	global_load_dwordx4 v[8:11], v[36:37], off
	v_lshl_add_u64 v[36:37], s[0:1], 0, v[124:125]
	v_mad_u64_u32 v[38:39], s[10:11], v36, s72, v[40:41]
	v_mad_i32_i24 v39, v37, s72, v39
	v_lshl_add_u64 v[36:37], v[38:39], 0, s[20:21]
	v_lshl_add_u64 v[36:37], v[36:37], 0, v[2:3]
	v_add_co_u32_e32 v36, vcc, s3, v36
	s_nop 1
	v_addc_co_u32_e32 v37, vcc, 0, v37, vcc
	global_load_dwordx4 v[12:15], v[36:37], off
	v_lshl_add_u64 v[36:37], s[0:1], 0, v[126:127]
	v_mad_u64_u32 v[38:39], s[0:1], v36, s72, v[40:41]
	v_mad_i32_i24 v39, v37, s72, v39
	v_lshl_add_u64 v[36:37], v[38:39], 0, s[20:21]
	v_lshl_add_u64 v[36:37], v[36:37], 0, v[2:3]
	v_add_co_u32_e32 v36, vcc, 0x1000, v36
	s_nop 1
	v_addc_co_u32_e32 v37, vcc, 0, v37, vcc
	global_load_dwordx4 v[16:19], v[36:37], off
	global_load_dwordx4 v[20:23], v[142:143], off
	global_load_dwordx4 v[24:27], v[144:145], off
	s_barrier
	v_add_u32_e32 v52, v133, v170
	v_mov_b32_e32 v44, v156
	v_mov_b32_e32 v45, v135
	v_mov_b32_e32 v40, 0
	s_mov_b32 s0, 16
	v_mov_b32_e32 v41, v40
	v_mov_b32_e32 v42, v40
	v_mov_b32_e32 v43, v40
	s_waitcnt vmcnt(5)
	ds_write_b128 v52, v[4:7]
	s_waitcnt vmcnt(4)
	ds_write_b128 v188, v[8:11]
	s_waitcnt vmcnt(3)
	ds_write_b128 v189, v[12:15]
	s_waitcnt vmcnt(2)
	ds_write_b128 v190, v[16:19]
	s_waitcnt vmcnt(1)
	ds_write_b128 v171, v[20:23]
	s_waitcnt vmcnt(0)
	ds_write_b128 v175, v[24:27]
	v_mov_b32_e32 v38, v40
	v_mov_b32_e32 v39, v40
	v_mov_b32_e32 v36, v40
	v_mov_b32_e32 v37, v40
	s_waitcnt lgkmcnt(0)
	s_barrier
	v_mov_b32_e32 v202, v45
	v_add_u32_e32 v203, 0x11000, v44
	ds_read_b128 v[4:7], v202
	ds_read_b128 v[8:11], v202 offset:16
	ds_read_b128 v[12:15], v203
	ds_read_b128 v[16:19], v203 offset:16
	ds_read_b128 v[20:23], v203 offset:512
	ds_read_b128 v[24:27], v203 offset:528
	ds_read_b128 v[28:31], v203 offset:1024
	ds_read_b128 v[32:35], v203 offset:1040
	ds_read_b128 v[88:91], v203 offset:1536
	ds_read_b128 v[92:95], v203 offset:1552
	ds_read_b128 v[96:99], v203 offset:2576
	ds_read_b128 v[100:103], v203 offset:2560
.LBB0_94:
	v_add_u32_e32 v50, 0, v45
	v_add_u32_e32 v53, 0, v44
	ds_read_b128 v[104:107], v203 offset:2048
	s_waitcnt lgkmcnt(12)
	v_mov_b64_e32 v[46:47], v[4:5]
	v_mov_b64_e32 v[48:49], v[6:7]
	ds_read_b128 v[108:111], v203 offset:2064
	s_waitcnt lgkmcnt(12)
	v_mov_b64_e32 v[54:55], v[8:9]
	v_mov_b64_e32 v[56:57], v[10:11]
	v_add_u32_e32 v50, 0x11000, v53
	ds_read_b128 v[112:115], v203 offset:3072
	s_waitcnt lgkmcnt(12)
	v_mov_b64_e32 v[58:59], v[12:13]
	v_mov_b64_e32 v[60:61], v[14:15]
	v_add_u32_e32 v50, 0x11010, v53
	ds_read_b128 v[194:197], v203 offset:3088
	s_waitcnt lgkmcnt(12)
	v_mov_b64_e32 v[62:63], v[16:17]
	v_mov_b64_e32 v[64:65], v[18:19]
	v_add_u32_e32 v50, 0x11200, v53
	ds_read_b128 v[198:201], v203 offset:3584
	s_waitcnt lgkmcnt(12)
	v_mov_b64_e32 v[66:67], v[20:21]
	v_mov_b64_e32 v[68:69], v[22:23]
	v_add_u32_e32 v50, 0x11210, v53
	v_and_b32_e32 v51, 0xffff0000, v46
	ds_read_b128 v[4:7], v203 offset:3600
	s_waitcnt lgkmcnt(12)
	v_mov_b64_e32 v[70:71], v[24:25]
	v_mov_b64_e32 v[72:73], v[26:27]
	v_and_b32_e32 v50, 16, v46
	v_lshlrev_b32_e32 v74, 16, v46
	v_mov_b32_e32 v75, v51
	v_and_b32_e32 v77, 0xffff0000, v47
	v_and_b32_e32 v83, 0xffff0000, v49
	v_and_b32_e32 v82, 16, v49
	v_lshlrev_b32_e32 v84, 16, v49
	v_mov_b32_e32 v49, v59
	v_pk_mov_b32 v[58:59], v[66:67], v[58:59] op_sel:[1,0]
	v_pk_mov_b32 v[50:51], v[50:51], v[74:75] op_sel:[1,0]
	v_and_b32_e32 v76, 16, v47
	v_lshlrev_b32_e32 v78, 16, v47
	v_mov_b32_e32 v79, v77
	v_and_b32_e32 v47, 0xffff0000, v48
	v_and_b32_e32 v46, 16, v48
	v_lshlrev_b32_e32 v80, 16, v48
	v_mov_b32_e32 v48, v66
	v_pk_mul_f32 v[58:59], v[58:59], v[50:51]
	v_pk_mov_b32 v[76:77], v[76:77], v[78:79] op_sel:[1,0]
	v_pk_fma_f32 v[48:49], v[48:49], v[74:75], v[58:59]
	v_mov_b32_e32 v59, v61
	v_pk_mov_b32 v[60:61], v[68:69], v[60:61] op_sel:[1,0]
	v_mov_b32_e32 v58, v68
	v_pk_mul_f32 v[60:61], v[60:61], v[76:77]
	v_mov_b32_e32 v81, v47
	v_pk_fma_f32 v[58:59], v[58:59], v[78:79], v[60:61]
	v_pk_mov_b32 v[60:61], v[70:71], v[62:63] op_sel:[1,0]
	v_pk_add_f32 v[48:49], v[48:49], v[58:59]
	v_mov_b32_e32 v58, v70
	v_pk_mov_b32 v[70:71], v[46:47], v[80:81] op_sel:[1,0]
	v_mov_b32_e32 v59, v63
	v_pk_mul_f32 v[46:47], v[60:61], v[70:71]
	v_mov_b32_e32 v85, v83
	v_pk_fma_f32 v[46:47], v[58:59], v[80:81], v[46:47]
	v_pk_mov_b32 v[58:59], v[72:73], v[64:65] op_sel:[1,0]
	v_pk_add_f32 v[46:47], v[48:49], v[46:47]
	v_mov_b32_e32 v48, v72
	v_pk_mov_b32 v[72:73], v[82:83], v[84:85] op_sel:[1,0]
	v_mov_b32_e32 v49, v65
	v_pk_mul_f32 v[58:59], v[58:59], v[72:73]
	s_add_i32 s0, s0, -2
	v_pk_fma_f32 v[48:49], v[48:49], v[84:85], v[58:59]
	v_add_u32_e32 v45, 32, v45
	v_pk_add_f32 v[46:47], v[48:49], v[46:47]
	v_add_u32_e32 v44, 64, v44
	v_pk_add_f32 v[82:83], v[40:41], v[46:47]
	v_add_u32_e32 v40, 0x11400, v53
	ds_read_b128 v[8:11], v203 offset:560
	s_waitcnt lgkmcnt(12)
	v_mov_b64_e32 v[46:47], v[28:29]
	v_mov_b64_e32 v[48:49], v[30:31]
	v_add_u32_e32 v40, 0x11410, v53
	ds_read_b128 v[12:15], v203 offset:544
	s_waitcnt lgkmcnt(12)
	v_mov_b64_e32 v[58:59], v[32:33]
	v_mov_b64_e32 v[60:61], v[34:35]
	v_add_u32_e32 v40, 0x11600, v53
	ds_read_b128 v[16:19], v203 offset:32
	s_waitcnt lgkmcnt(12)
	v_mov_b64_e32 v[62:63], v[88:89]
	v_mov_b64_e32 v[64:65], v[90:91]
	v_add_u32_e32 v40, 0x11610, v53
	ds_read_b128 v[20:23], v203 offset:48
	s_waitcnt lgkmcnt(12)
	v_mov_b64_e32 v[66:67], v[92:93]
	v_mov_b64_e32 v[68:69], v[94:95]
	s_cmp_lg_u32 s0, 0
	v_pk_mov_b32 v[40:41], v[46:47], v[62:63] op_sel:[1,0]
	v_mov_b32_e32 v47, v63
	v_pk_mul_f32 v[46:47], v[46:47], v[74:75]
	v_add_u32_e32 v62, 0x11a10, v53
	v_pk_fma_f32 v[40:41], v[40:41], v[50:51], v[46:47]
	v_pk_mov_b32 v[46:47], v[48:49], v[64:65] op_sel:[1,0]
	v_mov_b32_e32 v49, v65
	v_pk_mul_f32 v[48:49], v[48:49], v[78:79]
	ds_read_b128 v[24:27], v203 offset:1072
	s_waitcnt lgkmcnt(12)
	v_mov_b64_e32 v[62:63], v[96:97]
	v_mov_b64_e32 v[64:65], v[98:99]
	v_pk_fma_f32 v[46:47], v[46:47], v[76:77], v[48:49]
	s_nop 0
	v_pk_add_f32 v[40:41], v[40:41], v[46:47]
	v_pk_mov_b32 v[46:47], v[58:59], v[66:67] op_sel:[1,0]
	v_mov_b32_e32 v59, v67
	v_pk_mul_f32 v[48:49], v[58:59], v[80:81]
	v_add_u32_e32 v58, 0x11a00, v53
	v_pk_fma_f32 v[46:47], v[46:47], v[70:71], v[48:49]
	s_nop 0
	v_pk_add_f32 v[40:41], v[40:41], v[46:47]
	v_pk_mov_b32 v[46:47], v[60:61], v[68:69] op_sel:[1,0]
	v_mov_b32_e32 v61, v69
	v_pk_mul_f32 v[48:49], v[60:61], v[84:85]
	ds_read_b128 v[28:31], v203 offset:1056
	s_waitcnt lgkmcnt(12)
	v_mov_b64_e32 v[58:59], v[100:101]
	v_mov_b64_e32 v[60:61], v[102:103]
	v_pk_fma_f32 v[46:47], v[46:47], v[72:73], v[48:49]
	s_nop 0
	v_pk_add_f32 v[40:41], v[46:47], v[40:41]
	v_add_u32_e32 v46, 0x11810, v53
	v_pk_add_f32 v[66:67], v[42:43], v[40:41]
	v_add_u32_e32 v40, 0x11800, v53
	ds_read_b128 v[32:35], v203 offset:1568
	s_waitcnt lgkmcnt(12)
	v_mov_b64_e32 v[40:41], v[104:105]
	v_mov_b64_e32 v[42:43], v[106:107]
	ds_read_b128 v[88:91], v203 offset:1584
	s_waitcnt lgkmcnt(12)
	v_mov_b64_e32 v[46:47], v[108:109]
	v_mov_b64_e32 v[48:49], v[110:111]
	v_pk_mov_b32 v[68:69], v[40:41], v[58:59] op_sel:[1,0]
	v_mov_b32_e32 v41, v59
	v_pk_mov_b32 v[58:59], v[42:43], v[60:61] op_sel:[1,0]
	v_mov_b32_e32 v43, v61
	v_pk_mul_f32 v[40:41], v[40:41], v[74:75]
	v_pk_mul_f32 v[42:43], v[42:43], v[78:79]
	v_pk_fma_f32 v[40:41], v[68:69], v[50:51], v[40:41]
	v_pk_fma_f32 v[42:43], v[58:59], v[76:77], v[42:43]
	s_nop 0
	v_pk_add_f32 v[40:41], v[40:41], v[42:43]
	v_pk_mov_b32 v[42:43], v[46:47], v[62:63] op_sel:[1,0]
	v_mov_b32_e32 v47, v63
	v_pk_mul_f32 v[46:47], v[46:47], v[80:81]
	s_nop 0
	v_pk_fma_f32 v[42:43], v[42:43], v[70:71], v[46:47]
	s_nop 0
	v_pk_add_f32 v[40:41], v[40:41], v[42:43]
	v_pk_mov_b32 v[42:43], v[48:49], v[64:65] op_sel:[1,0]
	v_mov_b32_e32 v49, v65
	v_pk_mul_f32 v[46:47], v[48:49], v[84:85]
	s_nop 0
	v_pk_fma_f32 v[42:43], v[42:43], v[72:73], v[46:47]
	s_nop 0
	v_pk_add_f32 v[40:41], v[42:43], v[40:41]
	v_add_u32_e32 v42, 0x11c10, v53
	v_pk_add_f32 v[68:69], v[38:39], v[40:41]
	v_add_u32_e32 v38, 0x11c00, v53
	ds_read_b128 v[92:95], v203 offset:2592
	s_waitcnt lgkmcnt(12)
	v_mov_b64_e32 v[38:39], v[112:113]
	v_mov_b64_e32 v[40:41], v[114:115]
	ds_read_b128 v[96:99], v203 offset:2096
	s_waitcnt lgkmcnt(12)
	v_mov_b64_e32 v[46:47], v[194:195]
	v_mov_b64_e32 v[48:49], v[196:197]
	v_add_u32_e32 v42, 0x11e00, v53
	ds_read_b128 v[100:103], v203 offset:2608
	s_waitcnt lgkmcnt(12)
	v_mov_b64_e32 v[58:59], v[198:199]
	v_mov_b64_e32 v[60:61], v[200:201]
	v_add_u32_e32 v42, 0x11e10, v53
	ds_read_b128 v[104:107], v203 offset:2080
	s_waitcnt lgkmcnt(12)
	v_mov_b64_e32 v[62:63], v[4:5]
	v_mov_b64_e32 v[64:65], v[6:7]
	v_pk_mov_b32 v[42:43], v[38:39], v[58:59] op_sel:[1,0]
	v_mov_b32_e32 v39, v59
	v_pk_mul_f32 v[38:39], v[38:39], v[74:75]
	v_add_u32_e32 v58, 0x11230, v53
	v_pk_fma_f32 v[38:39], v[42:43], v[50:51], v[38:39]
	v_pk_mov_b32 v[42:43], v[40:41], v[60:61] op_sel:[1,0]
	v_mov_b32_e32 v41, v61
	v_pk_mul_f32 v[40:41], v[40:41], v[78:79]
	ds_read_b128 v[108:111], v203 offset:3104
	s_waitcnt lgkmcnt(12)
	v_mov_b64_e32 v[58:59], v[8:9]
	v_mov_b64_e32 v[60:61], v[10:11]
	v_pk_fma_f32 v[40:41], v[42:43], v[76:77], v[40:41]
	v_and_b32_e32 v77, 0xffff0000, v57
	v_pk_add_f32 v[38:39], v[38:39], v[40:41]
	v_pk_mov_b32 v[40:41], v[46:47], v[62:63] op_sel:[1,0]
	v_mov_b32_e32 v47, v63
	v_pk_mul_f32 v[42:43], v[46:47], v[80:81]
	v_add_u32_e32 v46, 0x11220, v53
	v_pk_fma_f32 v[40:41], v[40:41], v[70:71], v[42:43]
	v_and_b32_e32 v63, 0xffff0000, v54
	v_pk_add_f32 v[38:39], v[38:39], v[40:41]
	v_pk_mov_b32 v[40:41], v[48:49], v[64:65] op_sel:[1,0]
	v_mov_b32_e32 v49, v65
	v_pk_mul_f32 v[42:43], v[48:49], v[84:85]
	ds_read_b128 v[112:115], v203 offset:3120
	s_waitcnt lgkmcnt(12)
	v_mov_b64_e32 v[46:47], v[12:13]
	v_mov_b64_e32 v[48:49], v[14:15]
	v_pk_fma_f32 v[40:41], v[40:41], v[72:73], v[42:43]
	v_and_b32_e32 v65, 0xffff0000, v55
	v_pk_add_f32 v[38:39], v[40:41], v[38:39]
	v_add_u32_e32 v40, 0x11030, v53
	v_pk_add_f32 v[50:51], v[36:37], v[38:39]
	v_add_u32_e32 v36, 0x11020, v53
	ds_read_b128 v[194:197], v203 offset:3616
	s_waitcnt lgkmcnt(12)
	v_mov_b64_e32 v[36:37], v[16:17]
	v_mov_b64_e32 v[38:39], v[18:19]
	ds_read_b128 v[198:201], v203 offset:3632
	s_waitcnt lgkmcnt(12)
	v_mov_b64_e32 v[40:41], v[20:21]
	v_mov_b64_e32 v[42:43], v[22:23]
	v_and_b32_e32 v62, 16, v54
	v_lshlrev_b32_e32 v70, 16, v54
	v_mov_b32_e32 v71, v63
	v_and_b32_e32 v64, 16, v55
	v_lshlrev_b32_e32 v72, 16, v55
	v_mov_b32_e32 v73, v65
	v_and_b32_e32 v76, 16, v57
	v_lshlrev_b32_e32 v78, 16, v57
	v_mov_b32_e32 v57, v37
	v_pk_mov_b32 v[36:37], v[46:47], v[36:37] op_sel:[1,0]
	v_pk_mov_b32 v[80:81], v[62:63], v[70:71] op_sel:[1,0]
	v_mov_b32_e32 v47, v39
	v_pk_mov_b32 v[38:39], v[48:49], v[38:39] op_sel:[1,0]
	v_pk_mov_b32 v[84:85], v[64:65], v[72:73] op_sel:[1,0]
	v_and_b32_e32 v55, 0xffff0000, v56
	v_and_b32_e32 v54, 16, v56
	v_lshlrev_b32_e32 v74, 16, v56
	v_mov_b32_e32 v56, v46
	v_pk_mul_f32 v[36:37], v[36:37], v[80:81]
	v_mov_b32_e32 v46, v48
	v_pk_mul_f32 v[38:39], v[38:39], v[84:85]
	v_mov_b32_e32 v75, v55
	v_pk_fma_f32 v[36:37], v[56:57], v[70:71], v[36:37]
	v_pk_fma_f32 v[38:39], v[46:47], v[72:73], v[38:39]
	v_pk_mov_b32 v[86:87], v[54:55], v[74:75] op_sel:[1,0]
	v_pk_add_f32 v[36:37], v[36:37], v[38:39]
	v_mov_b32_e32 v39, v41
	v_pk_mov_b32 v[40:41], v[58:59], v[40:41] op_sel:[1,0]
	v_mov_b32_e32 v79, v77
	v_mov_b32_e32 v38, v58
	v_pk_mul_f32 v[40:41], v[40:41], v[86:87]
	v_pk_mov_b32 v[76:77], v[76:77], v[78:79] op_sel:[1,0]
	v_pk_fma_f32 v[38:39], v[38:39], v[74:75], v[40:41]
	v_pk_mov_b32 v[40:41], v[60:61], v[42:43] op_sel:[1,0]
	v_pk_add_f32 v[36:37], v[36:37], v[38:39]
	v_mov_b32_e32 v38, v60
	v_mov_b32_e32 v39, v43
	v_pk_mul_f32 v[40:41], v[40:41], v[76:77]
	v_add_u32_e32 v42, 0x11430, v53
	v_pk_fma_f32 v[38:39], v[38:39], v[78:79], v[40:41]
	ds_read_b128 v[4:7], v202 offset:32
	s_waitcnt lgkmcnt(12)
	v_mov_b64_e32 v[46:47], v[24:25]
	v_mov_b64_e32 v[48:49], v[26:27]
	v_pk_add_f32 v[36:37], v[38:39], v[36:37]
	v_add_u32_e32 v42, 0x11620, v53
	v_pk_add_f32 v[40:41], v[82:83], v[36:37]
	v_add_u32_e32 v36, 0x11420, v53
	ds_read_b128 v[8:11], v202 offset:48
	s_waitcnt lgkmcnt(12)
	v_mov_b64_e32 v[36:37], v[28:29]
	v_mov_b64_e32 v[38:39], v[30:31]
	ds_read_b128 v[12:15], v203 offset:64
	s_waitcnt lgkmcnt(12)
	v_mov_b64_e32 v[54:55], v[32:33]
	v_mov_b64_e32 v[56:57], v[34:35]
	v_add_u32_e32 v42, 0x11630, v53
	ds_read_b128 v[16:19], v203 offset:80
	s_waitcnt lgkmcnt(12)
	v_mov_b64_e32 v[58:59], v[88:89]
	v_mov_b64_e32 v[60:61], v[90:91]
	v_pk_mov_b32 v[42:43], v[36:37], v[54:55] op_sel:[1,0]
	v_mov_b32_e32 v37, v55
	v_pk_mul_f32 v[36:37], v[36:37], v[70:71]
	v_add_u32_e32 v54, 0x11a20, v53
	v_pk_fma_f32 v[36:37], v[42:43], v[80:81], v[36:37]
	v_pk_mov_b32 v[42:43], v[38:39], v[56:57] op_sel:[1,0]
	v_mov_b32_e32 v39, v57
	v_pk_mul_f32 v[38:39], v[38:39], v[72:73]
	ds_read_b128 v[20:23], v203 offset:576
	s_waitcnt lgkmcnt(12)
	v_mov_b64_e32 v[54:55], v[92:93]
	v_mov_b64_e32 v[56:57], v[94:95]
	v_pk_fma_f32 v[38:39], v[42:43], v[84:85], v[38:39]
	s_nop 0
	v_pk_add_f32 v[36:37], v[36:37], v[38:39]
	v_pk_mov_b32 v[38:39], v[46:47], v[58:59] op_sel:[1,0]
	v_mov_b32_e32 v47, v59
	v_pk_mul_f32 v[42:43], v[46:47], v[74:75]
	v_add_u32_e32 v46, 0x11830, v53
	v_pk_fma_f32 v[38:39], v[38:39], v[86:87], v[42:43]
	v_add_u32_e32 v58, 0x11a30, v53
	v_pk_add_f32 v[36:37], v[36:37], v[38:39]
	v_pk_mov_b32 v[38:39], v[48:49], v[60:61] op_sel:[1,0]
	v_mov_b32_e32 v49, v61
	v_pk_mul_f32 v[42:43], v[48:49], v[78:79]
	ds_read_b128 v[24:27], v203 offset:592
	s_waitcnt lgkmcnt(12)
	v_mov_b64_e32 v[46:47], v[96:97]
	v_mov_b64_e32 v[48:49], v[98:99]
	v_pk_fma_f32 v[38:39], v[38:39], v[76:77], v[42:43]
	ds_read_b128 v[28:31], v203 offset:1088
	s_waitcnt lgkmcnt(12)
	v_mov_b64_e32 v[58:59], v[100:101]
	v_mov_b64_e32 v[60:61], v[102:103]
	v_pk_add_f32 v[36:37], v[38:39], v[36:37]
	s_nop 0
	v_pk_add_f32 v[42:43], v[66:67], v[36:37]
	v_add_u32_e32 v36, 0x11820, v53
	ds_read_b128 v[32:35], v203 offset:1104
	s_waitcnt lgkmcnt(12)
	v_mov_b64_e32 v[36:37], v[104:105]
	v_mov_b64_e32 v[38:39], v[106:107]
	v_pk_mov_b32 v[62:63], v[36:37], v[54:55] op_sel:[1,0]
	v_mov_b32_e32 v37, v55
	v_pk_mov_b32 v[54:55], v[38:39], v[56:57] op_sel:[1,0]
	v_mov_b32_e32 v39, v57
	v_pk_mul_f32 v[36:37], v[36:37], v[70:71]
	v_pk_mul_f32 v[38:39], v[38:39], v[72:73]
	v_pk_fma_f32 v[36:37], v[62:63], v[80:81], v[36:37]
	v_pk_fma_f32 v[38:39], v[54:55], v[84:85], v[38:39]
	s_nop 0
	v_pk_add_f32 v[36:37], v[36:37], v[38:39]
	v_pk_mov_b32 v[38:39], v[46:47], v[58:59] op_sel:[1,0]
	v_mov_b32_e32 v47, v59
	v_pk_mul_f32 v[46:47], v[46:47], v[74:75]
	s_nop 0
	v_pk_fma_f32 v[38:39], v[38:39], v[86:87], v[46:47]
	s_nop 0
	v_pk_add_f32 v[36:37], v[36:37], v[38:39]
	v_pk_mov_b32 v[38:39], v[48:49], v[60:61] op_sel:[1,0]
	v_mov_b32_e32 v49, v61
	v_pk_mul_f32 v[46:47], v[48:49], v[78:79]
	s_nop 0
	v_pk_fma_f32 v[38:39], v[38:39], v[76:77], v[46:47]
	s_nop 0
	v_pk_add_f32 v[36:37], v[38:39], v[36:37]
	s_nop 0
	v_pk_add_f32 v[38:39], v[68:69], v[36:37]
	v_add_u32_e32 v36, 0x11c20, v53
	ds_read_b128 v[88:91], v203 offset:1600
	s_waitcnt lgkmcnt(12)
	v_mov_b64_e32 v[46:47], v[108:109]
	v_mov_b64_e32 v[48:49], v[110:111]
	v_add_u32_e32 v36, 0x11c30, v53
	ds_read_b128 v[92:95], v203 offset:1616
	s_waitcnt lgkmcnt(12)
	v_mov_b64_e32 v[54:55], v[112:113]
	v_mov_b64_e32 v[56:57], v[114:115]
	v_add_u32_e32 v36, 0x11e20, v53
	ds_read_b128 v[96:99], v203 offset:2640
	s_waitcnt lgkmcnt(12)
	v_mov_b64_e32 v[58:59], v[194:195]
	v_mov_b64_e32 v[60:61], v[196:197]
	v_add_u32_e32 v36, 0x11e30, v53
	ds_read_b128 v[100:103], v203 offset:2624
	s_waitcnt lgkmcnt(12)
	v_mov_b64_e32 v[62:63], v[198:199]
	v_mov_b64_e32 v[64:65], v[200:201]
	v_pk_mov_b32 v[36:37], v[46:47], v[58:59] op_sel:[1,0]
	v_mov_b32_e32 v47, v59
	v_pk_mul_f32 v[46:47], v[46:47], v[70:71]
	s_nop 0
	v_pk_fma_f32 v[36:37], v[36:37], v[80:81], v[46:47]
	v_pk_mov_b32 v[46:47], v[48:49], v[60:61] op_sel:[1,0]
	v_mov_b32_e32 v49, v61
	v_pk_mul_f32 v[48:49], v[48:49], v[72:73]
	s_nop 0
	v_pk_fma_f32 v[46:47], v[46:47], v[84:85], v[48:49]
	s_nop 0
	v_pk_add_f32 v[36:37], v[36:37], v[46:47]
	v_pk_mov_b32 v[46:47], v[54:55], v[62:63] op_sel:[1,0]
	v_mov_b32_e32 v55, v63
	v_pk_mul_f32 v[48:49], v[54:55], v[74:75]
	s_nop 0
	v_pk_fma_f32 v[46:47], v[46:47], v[86:87], v[48:49]
	s_nop 0
	v_pk_add_f32 v[36:37], v[36:37], v[46:47]
	v_pk_mov_b32 v[46:47], v[56:57], v[64:65] op_sel:[1,0]
	v_mov_b32_e32 v57, v65
	v_pk_mul_f32 v[48:49], v[56:57], v[78:79]
	s_nop 0
	v_pk_fma_f32 v[46:47], v[46:47], v[76:77], v[48:49]
	s_nop 0
	v_pk_add_f32 v[36:37], v[46:47], v[36:37]
	s_nop 0
	v_pk_add_f32 v[36:37], v[50:51], v[36:37]
	v_add_u32_e32 v202, 32, v202
	v_add_u32_e32 v203, 64, v203
	s_cbranch_scc1 .LBB0_94
	s_ashr_i32 s47, s8, 1
	v_cmp_gt_i32_e32 vcc, s47, v128
	s_nop 1
	v_cndmask_b32_e32 v40, v215, v40, vcc
	v_cmp_gt_i32_e32 vcc, s47, v1
	s_nop 1
	v_cndmask_b32_e32 v41, v215, v41, vcc
	v_cmp_gt_i32_e32 vcc, s47, v121
	ds_write2_b32 v184, v41, v40 offset1:1
	s_nop 0
	v_cndmask_b32_e32 v40, v215, v43, vcc
	v_cmp_gt_i32_e32 vcc, s47, v130
	s_nop 1
	v_cndmask_b32_e32 v41, v215, v42, vcc
	v_cmp_gt_i32_e32 vcc, s47, v129
	ds_write2_b32 v185, v41, v40 offset1:1
	s_nop 0
	v_cndmask_b32_e32 v39, v215, v39, vcc
	v_cmp_gt_i32_e32 vcc, s47, v132
	s_nop 1
	v_cndmask_b32_e32 v38, v215, v38, vcc
	v_cmp_gt_i32_e32 vcc, s47, v131
	ds_write2_b32 v186, v38, v39 offset1:1
	s_nop 0
	v_cndmask_b32_e32 v37, v215, v37, vcc
	v_cmp_gt_i32_e32 vcc, s47, v134
	s_nop 1
	v_cndmask_b32_e32 v36, v215, v36, vcc
	ds_write2_b32 v187, v36, v37 offset1:1
	s_waitcnt lgkmcnt(0)
	s_barrier
	s_and_saveexec_b64 s[0:1], s[4:5]
	s_cbranch_execz .LBB0_97
	ds_read2_b32 v[36:37], v191 offset1:1
	ds_read2_b32 v[38:39], v191 offset0:2 offset1:3
	ds_read2_b32 v[40:41], v191 offset0:4 offset1:5
	ds_read2_b32 v[42:43], v191 offset0:6 offset1:7
	ds_read2_b32 v[44:45], v191 offset0:8 offset1:9
	ds_read2_b32 v[46:47], v191 offset0:10 offset1:11
	ds_read2_b32 v[48:49], v191 offset0:12 offset1:13
	ds_read2_b32 v[50:51], v191 offset0:14 offset1:15
	ds_read2_b32 v[54:55], v191 offset0:16 offset1:17
	ds_read2_b32 v[56:57], v191 offset0:18 offset1:19
	ds_read2_b32 v[58:59], v191 offset0:20 offset1:21
	ds_read2_b32 v[60:61], v191 offset0:22 offset1:23
	ds_read2_b32 v[62:63], v191 offset0:24 offset1:25
	ds_read2_b32 v[64:65], v191 offset0:26 offset1:27
	ds_read2_b32 v[66:67], v191 offset0:28 offset1:29
	ds_read2_b32 v[68:69], v191 offset0:30 offset1:31
	s_waitcnt lgkmcnt(14)
	v_cmp_nlg_f32_e32 vcc, s73, v36
	s_nop 1
	v_cndmask_b32_e32 v70, v36, v215, vcc
	v_cndmask_b32_e64 v53, 0, -1, vcc
	v_cmp_gt_f32_e32 vcc, v37, v70
	s_nop 1
	v_cndmask_b32_e32 v70, v70, v37, vcc
	v_cndmask_b32_e64 v53, v53, 1, vcc
	v_cmp_gt_f32_e32 vcc, v38, v70
	s_nop 1
	v_cndmask_b32_e32 v70, v70, v38, vcc
	v_cndmask_b32_e64 v53, v53, 2, vcc
	v_cmp_gt_f32_e32 vcc, v39, v70
	s_nop 1
	v_cndmask_b32_e32 v70, v70, v39, vcc
	v_cndmask_b32_e64 v53, v53, 3, vcc
	s_waitcnt lgkmcnt(13)
	v_cmp_gt_f32_e32 vcc, v40, v70
	s_nop 1
	v_cndmask_b32_e32 v70, v70, v40, vcc
	v_cndmask_b32_e64 v53, v53, 4, vcc
	v_cmp_gt_f32_e32 vcc, v41, v70
	s_nop 1
	v_cndmask_b32_e32 v70, v70, v41, vcc
	v_cndmask_b32_e64 v53, v53, 5, vcc
	s_waitcnt lgkmcnt(12)
	v_cmp_gt_f32_e32 vcc, v42, v70
	s_nop 1
	v_cndmask_b32_e32 v70, v70, v42, vcc
	v_cndmask_b32_e64 v53, v53, 6, vcc
	v_cmp_gt_f32_e32 vcc, v43, v70
	s_nop 1
	v_cndmask_b32_e32 v70, v70, v43, vcc
	v_cndmask_b32_e64 v53, v53, 7, vcc
	s_waitcnt lgkmcnt(11)
	v_cmp_gt_f32_e32 vcc, v44, v70
	s_nop 1
	v_cndmask_b32_e32 v70, v70, v44, vcc
	v_cndmask_b32_e64 v53, v53, 8, vcc
	v_cmp_gt_f32_e32 vcc, v45, v70
	s_nop 1
	v_cndmask_b32_e32 v70, v70, v45, vcc
	v_cndmask_b32_e64 v53, v53, 9, vcc
	s_waitcnt lgkmcnt(10)
	v_cmp_gt_f32_e32 vcc, v46, v70
	s_nop 1
	v_cndmask_b32_e32 v70, v70, v46, vcc
	v_cndmask_b32_e64 v53, v53, 10, vcc
	v_cmp_gt_f32_e32 vcc, v47, v70
	s_nop 1
	v_cndmask_b32_e32 v70, v70, v47, vcc
	v_cndmask_b32_e64 v53, v53, 11, vcc
	s_waitcnt lgkmcnt(9)
	v_cmp_gt_f32_e32 vcc, v48, v70
	s_nop 1
	v_cndmask_b32_e32 v70, v70, v48, vcc
	v_cndmask_b32_e64 v53, v53, 12, vcc
	v_cmp_gt_f32_e32 vcc, v49, v70
	s_nop 1
	v_cndmask_b32_e32 v70, v70, v49, vcc
	v_cndmask_b32_e64 v53, v53, 13, vcc
	s_waitcnt lgkmcnt(8)
	v_cmp_gt_f32_e32 vcc, v50, v70
	s_nop 1
	v_cndmask_b32_e32 v70, v70, v50, vcc
	v_cndmask_b32_e64 v53, v53, 14, vcc
	v_cmp_gt_f32_e32 vcc, v51, v70
	s_nop 1
	v_cndmask_b32_e32 v70, v70, v51, vcc
	v_cndmask_b32_e64 v53, v53, 15, vcc
	s_waitcnt lgkmcnt(7)
	v_cmp_gt_f32_e32 vcc, v54, v70
	s_nop 1
	v_cndmask_b32_e32 v70, v70, v54, vcc
	v_cndmask_b32_e64 v53, v53, 16, vcc
	v_cmp_gt_f32_e32 vcc, v55, v70
	s_nop 1
	v_cndmask_b32_e32 v70, v70, v55, vcc
	v_cndmask_b32_e64 v53, v53, 17, vcc
	s_waitcnt lgkmcnt(6)
	v_cmp_gt_f32_e32 vcc, v56, v70
	s_nop 1
	v_cndmask_b32_e32 v70, v70, v56, vcc
	v_cndmask_b32_e64 v53, v53, 18, vcc
	v_cmp_gt_f32_e32 vcc, v57, v70
	s_nop 1
	v_cndmask_b32_e32 v70, v70, v57, vcc
	v_cndmask_b32_e64 v53, v53, 19, vcc
	s_waitcnt lgkmcnt(5)
	v_cmp_gt_f32_e32 vcc, v58, v70
	s_nop 1
	v_cndmask_b32_e32 v70, v70, v58, vcc
	v_cndmask_b32_e64 v53, v53, 20, vcc
	v_cmp_gt_f32_e32 vcc, v59, v70
	s_nop 1
	v_cndmask_b32_e32 v70, v70, v59, vcc
	v_cndmask_b32_e64 v53, v53, 21, vcc
	s_waitcnt lgkmcnt(4)
	v_cmp_gt_f32_e32 vcc, v60, v70
	s_nop 1
	v_cndmask_b32_e32 v70, v70, v60, vcc
	v_cndmask_b32_e64 v53, v53, 22, vcc
	v_cmp_gt_f32_e32 vcc, v61, v70
	s_nop 1
	v_cndmask_b32_e32 v70, v70, v61, vcc
	v_cndmask_b32_e64 v53, v53, 23, vcc
	s_waitcnt lgkmcnt(3)
	v_cmp_gt_f32_e32 vcc, v62, v70
	s_nop 1
	v_cndmask_b32_e32 v70, v70, v62, vcc
	v_cndmask_b32_e64 v53, v53, 24, vcc
	v_cmp_gt_f32_e32 vcc, v63, v70
	s_nop 1
	v_cndmask_b32_e32 v70, v70, v63, vcc
	v_cndmask_b32_e64 v53, v53, 25, vcc
	s_waitcnt lgkmcnt(2)
	v_cmp_gt_f32_e32 vcc, v64, v70
	s_nop 1
	v_cndmask_b32_e32 v70, v70, v64, vcc
	v_cndmask_b32_e64 v53, v53, 26, vcc
	v_cmp_gt_f32_e32 vcc, v65, v70
	s_nop 1
	v_cndmask_b32_e32 v70, v70, v65, vcc
	v_cndmask_b32_e64 v53, v53, 27, vcc
	s_waitcnt lgkmcnt(1)
	v_cmp_gt_f32_e32 vcc, v66, v70
	s_nop 1
	v_cndmask_b32_e32 v70, v70, v66, vcc
	v_cndmask_b32_e64 v53, v53, 28, vcc
	v_cmp_gt_f32_e32 vcc, v67, v70
	s_nop 1
	v_cndmask_b32_e32 v70, v70, v67, vcc
	v_cndmask_b32_e64 v53, v53, 29, vcc
	s_waitcnt lgkmcnt(0)
	v_cmp_gt_f32_e32 vcc, v68, v70
	s_nop 1
	v_cndmask_b32_e32 v70, v70, v68, vcc
	v_cndmask_b32_e64 v53, v53, 30, vcc
	v_cmp_ngt_f32_e32 vcc, v69, v70
	s_nop 1
	v_cndmask_b32_e32 v53, 31, v53, vcc
	v_lshlrev_b32_e64 v70, v53, 1
	v_cmp_lt_i32_e32 vcc, -1, v53
	s_nop 1
	v_cndmask_b32_e32 v70, 0, v70, vcc
	v_cmp_ne_u32_e32 vcc, 0, v53
	s_nop 1
	v_cndmask_b32_e32 v36, v215, v36, vcc
	v_cmp_ne_u32_e32 vcc, 1, v53
	s_nop 1
	v_cndmask_b32_e32 v37, v215, v37, vcc
	v_cmp_ne_u32_e32 vcc, 2, v53
	s_nop 1
	v_cndmask_b32_e32 v38, v215, v38, vcc
	v_cmp_ne_u32_e32 vcc, 3, v53
	s_nop 1
	v_cndmask_b32_e32 v39, v215, v39, vcc
	v_cmp_ne_u32_e32 vcc, 4, v53
	s_nop 1
	v_cndmask_b32_e32 v40, v215, v40, vcc
	v_cmp_ne_u32_e32 vcc, 5, v53
	s_nop 1
	v_cndmask_b32_e32 v41, v215, v41, vcc
	v_cmp_ne_u32_e32 vcc, 6, v53
	s_nop 1
	v_cndmask_b32_e32 v42, v215, v42, vcc
	v_cmp_ne_u32_e32 vcc, 7, v53
	s_nop 1
	v_cndmask_b32_e32 v43, v215, v43, vcc
	v_cmp_ne_u32_e32 vcc, 8, v53
	s_nop 1
	v_cndmask_b32_e32 v44, v215, v44, vcc
	v_cmp_ne_u32_e32 vcc, 9, v53
	s_nop 1
	v_cndmask_b32_e32 v45, v215, v45, vcc
	v_cmp_ne_u32_e32 vcc, 10, v53
	s_nop 1
	v_cndmask_b32_e32 v46, v215, v46, vcc
	v_cmp_ne_u32_e32 vcc, 11, v53
	s_nop 1
	v_cndmask_b32_e32 v47, v215, v47, vcc
	v_cmp_ne_u32_e32 vcc, 12, v53
	s_nop 1
	v_cndmask_b32_e32 v48, v215, v48, vcc
	v_cmp_ne_u32_e32 vcc, 13, v53
	s_nop 1
	v_cndmask_b32_e32 v49, v215, v49, vcc
	v_cmp_ne_u32_e32 vcc, 14, v53
	s_nop 1
	v_cndmask_b32_e32 v50, v215, v50, vcc
	v_cmp_ne_u32_e32 vcc, 15, v53
	s_nop 1
	v_cndmask_b32_e32 v51, v215, v51, vcc
	v_cmp_ne_u32_e32 vcc, 16, v53
	s_nop 1
	v_cndmask_b32_e32 v54, v215, v54, vcc
	v_cmp_ne_u32_e32 vcc, 17, v53
	s_nop 1
	v_cndmask_b32_e32 v55, v215, v55, vcc
	v_cmp_ne_u32_e32 vcc, 18, v53
	s_nop 1
	v_cndmask_b32_e32 v56, v215, v56, vcc
	v_cmp_ne_u32_e32 vcc, 19, v53
	s_nop 1
	v_cndmask_b32_e32 v57, v215, v57, vcc
	v_cmp_ne_u32_e32 vcc, 20, v53
	s_nop 1
	v_cndmask_b32_e32 v58, v215, v58, vcc
	v_cmp_ne_u32_e32 vcc, 21, v53
	s_nop 1
	v_cndmask_b32_e32 v59, v215, v59, vcc
	v_cmp_ne_u32_e32 vcc, 22, v53
	s_nop 1
	v_cndmask_b32_e32 v60, v215, v60, vcc
	v_cmp_ne_u32_e32 vcc, 23, v53
	s_nop 1
	v_cndmask_b32_e32 v61, v215, v61, vcc
	v_cmp_ne_u32_e32 vcc, 24, v53
	s_nop 1
	v_cndmask_b32_e32 v62, v215, v62, vcc
	v_cmp_ne_u32_e32 vcc, 25, v53
	s_nop 1
	v_cndmask_b32_e32 v63, v215, v63, vcc
	v_cmp_ne_u32_e32 vcc, 26, v53
	s_nop 1
	v_cndmask_b32_e32 v64, v215, v64, vcc
	v_cmp_ne_u32_e32 vcc, 27, v53
	s_nop 1
	v_cndmask_b32_e32 v65, v215, v65, vcc
	v_cmp_ne_u32_e32 vcc, 28, v53
	s_nop 1
	v_cndmask_b32_e32 v66, v215, v66, vcc
	v_cmp_ne_u32_e32 vcc, 29, v53
	s_nop 1
	v_cndmask_b32_e32 v67, v215, v67, vcc
	v_cmp_ne_u32_e32 vcc, 30, v53
	s_nop 1
	v_cndmask_b32_e32 v68, v215, v68, vcc
	v_cmp_ne_u32_e32 vcc, 31, v53
	s_nop 1
	v_cndmask_b32_e32 v53, v215, v69, vcc
	v_cmp_nlg_f32_e32 vcc, s73, v36
	v_lshl_or_b32 v69, 1, s47, v70
	s_nop 0
	v_cndmask_b32_e32 v71, v36, v215, vcc
	v_cndmask_b32_e64 v70, 0, -1, vcc
	v_cmp_gt_f32_e32 vcc, v37, v71
	s_nop 1
	v_cndmask_b32_e32 v71, v71, v37, vcc
	v_cndmask_b32_e64 v70, v70, 1, vcc
	v_cmp_gt_f32_e32 vcc, v38, v71
	s_nop 1
	v_cndmask_b32_e32 v71, v71, v38, vcc
	v_cndmask_b32_e64 v70, v70, 2, vcc
	v_cmp_gt_f32_e32 vcc, v39, v71
	s_nop 1
	v_cndmask_b32_e32 v71, v71, v39, vcc
	v_cndmask_b32_e64 v70, v70, 3, vcc
	v_cmp_gt_f32_e32 vcc, v40, v71
	s_nop 1
	v_cndmask_b32_e32 v71, v71, v40, vcc
	v_cndmask_b32_e64 v70, v70, 4, vcc
	v_cmp_gt_f32_e32 vcc, v41, v71
	s_nop 1
	v_cndmask_b32_e32 v71, v71, v41, vcc
	v_cndmask_b32_e64 v70, v70, 5, vcc
	v_cmp_gt_f32_e32 vcc, v42, v71
	s_nop 1
	v_cndmask_b32_e32 v71, v71, v42, vcc
	v_cndmask_b32_e64 v70, v70, 6, vcc
	v_cmp_gt_f32_e32 vcc, v43, v71
	s_nop 1
	v_cndmask_b32_e32 v71, v71, v43, vcc
	v_cndmask_b32_e64 v70, v70, 7, vcc
	v_cmp_gt_f32_e32 vcc, v44, v71
	s_nop 1
	v_cndmask_b32_e32 v71, v71, v44, vcc
	v_cndmask_b32_e64 v70, v70, 8, vcc
	v_cmp_gt_f32_e32 vcc, v45, v71
	s_nop 1
	v_cndmask_b32_e32 v71, v71, v45, vcc
	v_cndmask_b32_e64 v70, v70, 9, vcc
	v_cmp_gt_f32_e32 vcc, v46, v71
	s_nop 1
	v_cndmask_b32_e32 v71, v71, v46, vcc
	v_cndmask_b32_e64 v70, v70, 10, vcc
	v_cmp_gt_f32_e32 vcc, v47, v71
	s_nop 1
	v_cndmask_b32_e32 v71, v71, v47, vcc
	v_cndmask_b32_e64 v70, v70, 11, vcc
	v_cmp_gt_f32_e32 vcc, v48, v71
	s_nop 1
	v_cndmask_b32_e32 v71, v71, v48, vcc
	v_cndmask_b32_e64 v70, v70, 12, vcc
	v_cmp_gt_f32_e32 vcc, v49, v71
	s_nop 1
	v_cndmask_b32_e32 v71, v71, v49, vcc
	v_cndmask_b32_e64 v70, v70, 13, vcc
	v_cmp_gt_f32_e32 vcc, v50, v71
	s_nop 1
	v_cndmask_b32_e32 v71, v71, v50, vcc
	v_cndmask_b32_e64 v70, v70, 14, vcc
	v_cmp_gt_f32_e32 vcc, v51, v71
	s_nop 1
	v_cndmask_b32_e32 v71, v71, v51, vcc
	v_cndmask_b32_e64 v70, v70, 15, vcc
	v_cmp_gt_f32_e32 vcc, v54, v71
	s_nop 1
	v_cndmask_b32_e32 v71, v71, v54, vcc
	v_cndmask_b32_e64 v70, v70, 16, vcc
	v_cmp_gt_f32_e32 vcc, v55, v71
	s_nop 1
	v_cndmask_b32_e32 v71, v71, v55, vcc
	v_cndmask_b32_e64 v70, v70, 17, vcc
	v_cmp_gt_f32_e32 vcc, v56, v71
	s_nop 1
	v_cndmask_b32_e32 v71, v71, v56, vcc
	v_cndmask_b32_e64 v70, v70, 18, vcc
	v_cmp_gt_f32_e32 vcc, v57, v71
	s_nop 1
	v_cndmask_b32_e32 v71, v71, v57, vcc
	v_cndmask_b32_e64 v70, v70, 19, vcc
	v_cmp_gt_f32_e32 vcc, v58, v71
	s_nop 1
	v_cndmask_b32_e32 v71, v71, v58, vcc
	v_cndmask_b32_e64 v70, v70, 20, vcc
	v_cmp_gt_f32_e32 vcc, v59, v71
	s_nop 1
	v_cndmask_b32_e32 v71, v71, v59, vcc
	v_cndmask_b32_e64 v70, v70, 21, vcc
	v_cmp_gt_f32_e32 vcc, v60, v71
	s_nop 1
	v_cndmask_b32_e32 v71, v71, v60, vcc
	v_cndmask_b32_e64 v70, v70, 22, vcc
	v_cmp_gt_f32_e32 vcc, v61, v71
	s_nop 1
	v_cndmask_b32_e32 v71, v71, v61, vcc
	v_cndmask_b32_e64 v70, v70, 23, vcc
	v_cmp_gt_f32_e32 vcc, v62, v71
	s_nop 1
	v_cndmask_b32_e32 v71, v71, v62, vcc
	v_cndmask_b32_e64 v70, v70, 24, vcc
	v_cmp_gt_f32_e32 vcc, v63, v71
	s_nop 1
	v_cndmask_b32_e32 v71, v71, v63, vcc
	v_cndmask_b32_e64 v70, v70, 25, vcc
	v_cmp_gt_f32_e32 vcc, v64, v71
	s_nop 1
	v_cndmask_b32_e32 v71, v71, v64, vcc
	v_cndmask_b32_e64 v70, v70, 26, vcc
	v_cmp_gt_f32_e32 vcc, v65, v71
	s_nop 1
	v_cndmask_b32_e32 v71, v71, v65, vcc
	v_cndmask_b32_e64 v70, v70, 27, vcc
	v_cmp_gt_f32_e32 vcc, v66, v71
	s_nop 1
	v_cndmask_b32_e32 v71, v71, v66, vcc
	v_cndmask_b32_e64 v70, v70, 28, vcc
	v_cmp_gt_f32_e32 vcc, v67, v71
	s_nop 1
	v_cndmask_b32_e32 v71, v71, v67, vcc
	v_cndmask_b32_e64 v70, v70, 29, vcc
	v_cmp_gt_f32_e32 vcc, v68, v71
	s_nop 1
	v_cndmask_b32_e32 v71, v71, v68, vcc
	v_cndmask_b32_e64 v70, v70, 30, vcc
	v_cmp_ngt_f32_e32 vcc, v53, v71
	s_nop 1
	v_cndmask_b32_e32 v70, 31, v70, vcc
	v_lshlrev_b32_e64 v71, v70, 1
	v_cmp_lt_i32_e32 vcc, -1, v70
	s_nop 1
	v_cndmask_b32_e32 v71, 0, v71, vcc
	v_cmp_ne_u32_e32 vcc, 0, v70
	s_nop 1
	v_cndmask_b32_e32 v36, v215, v36, vcc
	v_cmp_ne_u32_e32 vcc, 1, v70
	s_nop 1
	v_cndmask_b32_e32 v37, v215, v37, vcc
	v_cmp_ne_u32_e32 vcc, 2, v70
	s_nop 1
	v_cndmask_b32_e32 v38, v215, v38, vcc
	v_cmp_ne_u32_e32 vcc, 3, v70
	s_nop 1
	v_cndmask_b32_e32 v39, v215, v39, vcc
	v_cmp_ne_u32_e32 vcc, 4, v70
	s_nop 1
	v_cndmask_b32_e32 v40, v215, v40, vcc
	v_cmp_ne_u32_e32 vcc, 5, v70
	s_nop 1
	v_cndmask_b32_e32 v41, v215, v41, vcc
	v_cmp_ne_u32_e32 vcc, 6, v70
	s_nop 1
	v_cndmask_b32_e32 v42, v215, v42, vcc
	v_cmp_ne_u32_e32 vcc, 7, v70
	s_nop 1
	v_cndmask_b32_e32 v43, v215, v43, vcc
	v_cmp_ne_u32_e32 vcc, 8, v70
	s_nop 1
	v_cndmask_b32_e32 v44, v215, v44, vcc
	v_cmp_ne_u32_e32 vcc, 9, v70
	s_nop 1
	v_cndmask_b32_e32 v45, v215, v45, vcc
	v_cmp_ne_u32_e32 vcc, 10, v70
	s_nop 1
	v_cndmask_b32_e32 v46, v215, v46, vcc
	v_cmp_ne_u32_e32 vcc, 11, v70
	s_nop 1
	v_cndmask_b32_e32 v47, v215, v47, vcc
	v_cmp_ne_u32_e32 vcc, 12, v70
	s_nop 1
	v_cndmask_b32_e32 v48, v215, v48, vcc
	v_cmp_ne_u32_e32 vcc, 13, v70
	s_nop 1
	v_cndmask_b32_e32 v49, v215, v49, vcc
	v_cmp_ne_u32_e32 vcc, 14, v70
	s_nop 1
	v_cndmask_b32_e32 v50, v215, v50, vcc
	v_cmp_ne_u32_e32 vcc, 15, v70
	s_nop 1
	v_cndmask_b32_e32 v51, v215, v51, vcc
	v_cmp_ne_u32_e32 vcc, 16, v70
	s_nop 1
	v_cndmask_b32_e32 v54, v215, v54, vcc
	v_cmp_ne_u32_e32 vcc, 17, v70
	s_nop 1
	v_cndmask_b32_e32 v55, v215, v55, vcc
	v_cmp_ne_u32_e32 vcc, 18, v70
	s_nop 1
	v_cndmask_b32_e32 v56, v215, v56, vcc
	v_cmp_ne_u32_e32 vcc, 19, v70
	s_nop 1
	v_cndmask_b32_e32 v57, v215, v57, vcc
	v_cmp_ne_u32_e32 vcc, 20, v70
	s_nop 1
	v_cndmask_b32_e32 v58, v215, v58, vcc
	v_cmp_ne_u32_e32 vcc, 21, v70
	s_nop 1
	v_cndmask_b32_e32 v59, v215, v59, vcc
	v_cmp_ne_u32_e32 vcc, 22, v70
	s_nop 1
	v_cndmask_b32_e32 v60, v215, v60, vcc
	v_cmp_ne_u32_e32 vcc, 23, v70
	s_nop 1
	v_cndmask_b32_e32 v61, v215, v61, vcc
	v_cmp_ne_u32_e32 vcc, 24, v70
	s_nop 1
	v_cndmask_b32_e32 v62, v215, v62, vcc
	v_cmp_ne_u32_e32 vcc, 25, v70
	s_nop 1
	v_cndmask_b32_e32 v63, v215, v63, vcc
	v_cmp_ne_u32_e32 vcc, 26, v70
	s_nop 1
	v_cndmask_b32_e32 v64, v215, v64, vcc
	v_cmp_ne_u32_e32 vcc, 27, v70
	s_nop 1
	v_cndmask_b32_e32 v65, v215, v65, vcc
	v_cmp_ne_u32_e32 vcc, 28, v70
	s_nop 1
	v_cndmask_b32_e32 v66, v215, v66, vcc
	v_cmp_ne_u32_e32 vcc, 29, v70
	s_nop 1
	v_cndmask_b32_e32 v67, v215, v67, vcc
	v_cmp_ne_u32_e32 vcc, 30, v70
	s_nop 1
	v_cndmask_b32_e32 v68, v215, v68, vcc
	v_cmp_ne_u32_e32 vcc, 31, v70
	s_nop 1
	v_cndmask_b32_e32 v53, v215, v53, vcc
	v_cmp_nlg_f32_e32 vcc, s73, v36
	s_nop 1
	v_cndmask_b32_e32 v36, v36, v215, vcc
	v_cndmask_b32_e64 v70, 0, -1, vcc
	v_cmp_gt_f32_e32 vcc, v37, v36
	s_nop 1
	v_cndmask_b32_e32 v36, v36, v37, vcc
	v_cndmask_b32_e64 v70, v70, 1, vcc
	v_cmp_gt_f32_e32 vcc, v38, v36
	s_nop 1
	v_cndmask_b32_e32 v36, v36, v38, vcc
	v_cndmask_b32_e64 v37, v70, 2, vcc
	v_cmp_gt_f32_e32 vcc, v39, v36
	s_nop 1
	v_cndmask_b32_e32 v36, v36, v39, vcc
	v_cndmask_b32_e64 v37, v37, 3, vcc
	v_cmp_gt_f32_e32 vcc, v40, v36
	s_nop 1
	v_cndmask_b32_e32 v36, v36, v40, vcc
	v_cndmask_b32_e64 v37, v37, 4, vcc
	v_cmp_gt_f32_e32 vcc, v41, v36
	s_nop 1
	v_cndmask_b32_e32 v36, v36, v41, vcc
	v_cndmask_b32_e64 v37, v37, 5, vcc
	v_cmp_gt_f32_e32 vcc, v42, v36
	s_nop 1
	v_cndmask_b32_e32 v36, v36, v42, vcc
	v_cndmask_b32_e64 v37, v37, 6, vcc
	v_cmp_gt_f32_e32 vcc, v43, v36
	s_nop 1
	v_cndmask_b32_e32 v36, v36, v43, vcc
	v_cndmask_b32_e64 v37, v37, 7, vcc
	v_cmp_gt_f32_e32 vcc, v44, v36
	s_nop 1
	v_cndmask_b32_e32 v36, v36, v44, vcc
	v_cndmask_b32_e64 v37, v37, 8, vcc
	v_cmp_gt_f32_e32 vcc, v45, v36
	s_nop 1
	v_cndmask_b32_e32 v36, v36, v45, vcc
	v_cndmask_b32_e64 v37, v37, 9, vcc
	v_cmp_gt_f32_e32 vcc, v46, v36
	s_nop 1
	v_cndmask_b32_e32 v36, v36, v46, vcc
	v_cndmask_b32_e64 v37, v37, 10, vcc
	v_cmp_gt_f32_e32 vcc, v47, v36
	s_nop 1
	v_cndmask_b32_e32 v36, v36, v47, vcc
	v_cndmask_b32_e64 v37, v37, 11, vcc
	v_cmp_gt_f32_e32 vcc, v48, v36
	s_nop 1
	v_cndmask_b32_e32 v36, v36, v48, vcc
	v_cndmask_b32_e64 v37, v37, 12, vcc
	v_cmp_gt_f32_e32 vcc, v49, v36
	s_nop 1
	v_cndmask_b32_e32 v36, v36, v49, vcc
	v_cndmask_b32_e64 v37, v37, 13, vcc
	v_cmp_gt_f32_e32 vcc, v50, v36
	s_nop 1
	v_cndmask_b32_e32 v36, v36, v50, vcc
	v_cndmask_b32_e64 v37, v37, 14, vcc
	v_cmp_gt_f32_e32 vcc, v51, v36
	s_nop 1
	v_cndmask_b32_e32 v36, v36, v51, vcc
	v_cndmask_b32_e64 v37, v37, 15, vcc
	v_cmp_gt_f32_e32 vcc, v54, v36
	s_nop 1
	v_cndmask_b32_e32 v36, v36, v54, vcc
	v_cndmask_b32_e64 v37, v37, 16, vcc
	v_cmp_gt_f32_e32 vcc, v55, v36
	s_nop 1
	v_cndmask_b32_e32 v36, v36, v55, vcc
	v_cndmask_b32_e64 v37, v37, 17, vcc
	v_cmp_gt_f32_e32 vcc, v56, v36
	s_nop 1
	v_cndmask_b32_e32 v36, v36, v56, vcc
	v_cndmask_b32_e64 v37, v37, 18, vcc
	v_cmp_gt_f32_e32 vcc, v57, v36
	s_nop 1
	v_cndmask_b32_e32 v36, v36, v57, vcc
	v_cndmask_b32_e64 v37, v37, 19, vcc
	v_cmp_gt_f32_e32 vcc, v58, v36
	s_nop 1
	v_cndmask_b32_e32 v36, v36, v58, vcc
	v_cndmask_b32_e64 v37, v37, 20, vcc
	v_cmp_gt_f32_e32 vcc, v59, v36
	s_nop 1
	v_cndmask_b32_e32 v36, v36, v59, vcc
	v_cndmask_b32_e64 v37, v37, 21, vcc
	v_cmp_gt_f32_e32 vcc, v60, v36
	s_nop 1
	v_cndmask_b32_e32 v36, v36, v60, vcc
	v_cndmask_b32_e64 v37, v37, 22, vcc
	v_cmp_gt_f32_e32 vcc, v61, v36
	s_nop 1
	v_cndmask_b32_e32 v36, v36, v61, vcc
	v_cndmask_b32_e64 v37, v37, 23, vcc
	v_cmp_gt_f32_e32 vcc, v62, v36
	s_nop 1
	v_cndmask_b32_e32 v36, v36, v62, vcc
	v_cndmask_b32_e64 v37, v37, 24, vcc
	v_cmp_gt_f32_e32 vcc, v63, v36
	s_nop 1
	v_cndmask_b32_e32 v36, v36, v63, vcc
	v_cndmask_b32_e64 v37, v37, 25, vcc
	v_cmp_gt_f32_e32 vcc, v64, v36
	s_nop 1
	v_cndmask_b32_e32 v36, v36, v64, vcc
	v_cndmask_b32_e64 v37, v37, 26, vcc
	v_cmp_gt_f32_e32 vcc, v65, v36
	s_nop 1
	v_cndmask_b32_e32 v36, v36, v65, vcc
	v_cndmask_b32_e64 v37, v37, 27, vcc
	v_cmp_gt_f32_e32 vcc, v66, v36
	s_nop 1
	v_cndmask_b32_e32 v36, v36, v66, vcc
	v_cndmask_b32_e64 v37, v37, 28, vcc
	v_cmp_gt_f32_e32 vcc, v67, v36
	s_nop 1
	v_cndmask_b32_e32 v36, v36, v67, vcc
	v_cndmask_b32_e64 v37, v37, 29, vcc
	v_cmp_gt_f32_e32 vcc, v68, v36
	s_nop 1
	v_cndmask_b32_e32 v36, v36, v68, vcc
	v_cndmask_b32_e64 v37, v37, 30, vcc
	v_cmp_ngt_f32_e32 vcc, v53, v36
	s_nop 1
	v_cndmask_b32_e32 v36, 31, v37, vcc
	v_lshlrev_b32_e64 v37, v36, 1
	v_cmp_lt_i32_e32 vcc, -1, v36
	s_nop 1
	v_cndmask_b32_e32 v36, 0, v37, vcc
	v_or3_b32 v36, v69, v71, v36
	ds_write_b32 v166, v36
